# k20 + seam 0 relaxed: row-norm phase waits only for the 96 adaLN modulation items (own counter), not for every workgroup's prep items; seam 1 remains the full barrier
# baseline (speedup 1.0000x reference)
; __device__ void mod_item(const Params& p, int item, float* lds, int wave) {
;     ...
;     for (int b = 0; b < NB; ++b) lds[(kg * NB + b) * 64 + col] = acc[b];
;     __syncthreads();
;     for (int e = tid; e < NB * 64; e += NTHR) { const int b = e >> 6, cc = e & 63; float s = 0.f;
; #pragma unroll
;         for (int k = 0; k < 8; ++k) s += lds[(k * NB + b) * 64 + cc];
;         mod[b * MODW + col0 + cc] = s + p.ada_b[col0 + cc]; }
; }
; __device__ void phase_prep(const Params& p, float* lds, int wave) {
;     ...
;         else if (it < N_FILT_ITEMS + N_MOD_ITEMS) mod_item(p, it - N_FILT_ITEMS, lds, wave);
.LBB0_50:
	s_or_b64 exec, exec, s[0:1]
	s_waitcnt vmcnt(0)
	s_barrier
	s_cmp_gt_u32 s74, 63
	s_cbranch_scc1 .Lmodsig_done
	v_mbcnt_lo_u32_b32 v255, -1, 0
	v_mbcnt_hi_u32_b32 v255, -1, v255
	s_nop 0
	v_cmp_eq_u32_e32 vcc, 0, v255
	s_and_saveexec_b64 s[0:1], vcc
	s_cbranch_execz .Lmodsig_x
	buffer_wbl2 sc1
	s_waitcnt vmcnt(0)
	v_readlane_b32 s4, v253, 10
	v_readlane_b32 s5, v253, 11
	v_mov_b32_e32 v255, 0x4008
	v_mov_b32_e32 v251, 1
	s_nop 4
	global_atomic_add v255, v251, s[4:5]

; __device__ void phase_prep(const Params& p, float* lds, int wave) {
;     ...
;     for (int it = blockIdx.x; it < total; it += gridDim.x) {
;         if (it < N_FILT_ITEMS) { const bool longf = it < TS / 16; const int nx = it + gridDim.x;
;             const bool flush = !(nx < N_FILT_ITEMS && ((nx < TS / 16) == longf));
;             filt_item(p, longf ? 1 : 0, longf ? it : it - TS / 16, lds, wave, colsum, flush); }
;         else if (it < N_FILT_ITEMS + N_MOD_ITEMS) mod_item(p, it - N_FILT_ITEMS, lds, wave);
.Lmodsig_done:
.LBB0_51:
	s_mov_b64 s[0:1], 0

; #define PH(k) if (lo <= (k) && (k) < hi) for (int rep_ = 0; rep_ <= ((REP_MASK >> (k)) & 1); ++rep_)
; #define SEAM(k) if (lo <= (k) && (k) + 1 < hi) grid_bar(barctr, (unsigned)((k) + 1 - lo) * gridDim.x, wave)
; __device__ __forceinline__ void grid_bar(unsigned* ctr, unsigned target, int wave) {
;     __builtin_amdgcn_s_waitcnt(0x0F70);
;     __syncthreads();
;     if (wave == 0) {
;         int l; asm volatile("v_mbcnt_lo_u32_b32 %0, -1, 0\n\tv_mbcnt_hi_u32_b32 %0, -1, %0" : "=v"(l));
;         if (l == 0) {
;             __builtin_amdgcn_fence(__ATOMIC_RELEASE, "agent");
;             __hip_atomic_fetch_add(ctr, 1u, __ATOMIC_RELAXED, __HIP_MEMORY_SCOPE_AGENT);
;             while (__hip_atomic_load(ctr, __ATOMIC_RELAXED, __HIP_MEMORY_SCOPE_AGENT) < target) __builtin_amdgcn_s_sleep(2);
; __global__ void __launch_bounds__(NTHR, 2) fwd_kernel(Params p) {
;     ...
;     PH(0) { phase_prep(p, (float*)smem, wave); } SEAM(0);
.LBB0_143:
	s_or_b64 exec, exec, s[6:7]
	v_readlane_b32 s6, v253, 61
	v_mov_b32_e32 v0, 0
	v_readlane_b32 s7, v253, 62
	s_sub_i32 s3, 1, s72
	s_mul_i32 s3, s93, s3
	s_cmpk_lg_i32 s93, 0x100
	s_cbranch_scc1 .Lxb9_p
	s_movk_i32 s3, 0x60
	v_mov_b32_e32 v0, 8
